# phases with only 16-byte stores (combine0/out0/in1/combine1/out1) write through with sc1; their closing grid barriers skip the L2 write-back
# speedup vs baseline: 1.0073x; 1.0073x over previous
.LBB0_1038:
	s_andn2_saveexec_b64 s[10:11], s[10:11]
	s_cbranch_execz .LBB0_1058
	s_mov_b64 s[12:13], exec
	s_waitcnt lgkmcnt(0)
	v_mbcnt_lo_u32_b32 v1, s12, 0
	v_mbcnt_hi_u32_b32 v1, s13, v1
	v_cmp_eq_u32_e32 vcc, 0, v1
	s_and_saveexec_b64 s[16:17], vcc
	s_cbranch_execz .LBB0_1041
	s_bcnt1_i32_b64 s3, s[12:13]
	v_mov_b32_e32 v2, 0xed25000
	v_mov_b32_e32 v3, s3
	global_atomic_add v2, v2, v3, s[24:25] offset:1024 sc0

.LBB0_1104:
	s_andn2_saveexec_b64 s[6:7], s[6:7]
	s_cbranch_execz .LBB0_1124
	s_mov_b64 s[16:17], exec
	s_waitcnt lgkmcnt(0)
	v_mbcnt_lo_u32_b32 v1, s16, 0
	v_mbcnt_hi_u32_b32 v1, s17, v1
	v_cmp_eq_u32_e32 vcc, 0, v1
	s_and_saveexec_b64 s[28:29], vcc
	s_cbranch_execz .LBB0_1107
	s_bcnt1_i32_b64 s3, s[16:17]
	v_mov_b32_e32 v2, 0xed25000
	v_mov_b32_e32 v3, s3
	global_atomic_add v2, v2, v3, s[24:25] offset:1024 sc0

.LBB0_1267:
	s_and_b32 s18, s54, -4
	s_cmp_eq_u32 s18, 4
	s_cselect_b64 vcc, -1, 0
	v_or_b32_e32 v152, s47, v156
	v_cndmask_b32_e32 v150, 1.0, v165, vcc
	v_pk_mul_f32 v[124:125], v[150:151], v[124:125] op_sel_hi:[0,1]
	v_pk_mul_f32 v[120:121], v[150:151], v[120:121] op_sel_hi:[0,1]
	v_ashrrev_i32_e32 v153, 31, v152
	v_lshl_or_b32 v154, s54, 8, v158
	v_pk_mul_f32 v[166:167], v[150:151], v[122:123] op_sel_hi:[0,1]
	v_cvt_pk_bf16_f32 v122, v124, v125
	v_cvt_pk_bf16_f32 v124, v120, v121
	v_lshlrev_b64 v[120:121], 13, v[152:153]
	v_ashrrev_i32_e32 v155, 31, v154
	v_pk_mul_f32 v[126:127], v[150:151], v[126:127] op_sel_hi:[0,1]
	v_lshl_add_u64 v[120:121], s[60:61], 0, v[120:121]
	v_cvt_pk_bf16_f32 v123, v126, v127
	v_cvt_pk_bf16_f32 v125, v166, v167
	v_lshl_add_u64 v[120:121], v[154:155], 1, v[120:121]
	s_and_b64 vcc, exec, s[6:7]
	global_store_dwordx4 v[120:121], v[122:125], off sc1
	s_cbranch_vccnz .LBB0_1269
.LBB0_1269:
	v_mov_b32_e32 v151, v150
	v_or_b32_e32 v122, 16, v152
	v_pk_mul_f32 v[116:117], v[150:151], v[116:117]
	v_pk_mul_f32 v[112:113], v[150:151], v[112:113]
	v_ashrrev_i32_e32 v123, 31, v122
	v_pk_mul_f32 v[124:125], v[150:151], v[114:115]
	v_cvt_pk_bf16_f32 v114, v116, v117
	v_cvt_pk_bf16_f32 v116, v112, v113
	v_lshlrev_b64 v[112:113], 13, v[122:123]
	v_pk_mul_f32 v[118:119], v[150:151], v[118:119]
	v_lshl_add_u64 v[112:113], s[60:61], 0, v[112:113]
	v_cvt_pk_bf16_f32 v115, v118, v119
	v_cvt_pk_bf16_f32 v117, v124, v125
	v_lshl_add_u64 v[112:113], v[154:155], 1, v[112:113]
	s_and_b64 vcc, exec, s[6:7]
	global_store_dwordx4 v[112:113], v[114:117], off sc1
	s_cbranch_vccnz .LBB0_1271
.LBB0_1271:
	s_nop 0
	v_or_b32_e32 v114, 32, v152
	v_pk_mul_f32 v[108:109], v[150:151], v[108:109]
	v_pk_mul_f32 v[104:105], v[150:151], v[104:105]
	v_ashrrev_i32_e32 v115, 31, v114
	v_pk_mul_f32 v[116:117], v[150:151], v[106:107]
	v_cvt_pk_bf16_f32 v106, v108, v109
	v_cvt_pk_bf16_f32 v108, v104, v105
	v_lshlrev_b64 v[104:105], 13, v[114:115]
	v_pk_mul_f32 v[110:111], v[150:151], v[110:111]
	v_lshl_add_u64 v[104:105], s[60:61], 0, v[104:105]
	v_cvt_pk_bf16_f32 v107, v110, v111
	v_cvt_pk_bf16_f32 v109, v116, v117
	v_lshl_add_u64 v[104:105], v[154:155], 1, v[104:105]
	s_and_b64 vcc, exec, s[6:7]
	global_store_dwordx4 v[104:105], v[106:109], off sc1
	s_cbranch_vccnz .LBB0_1273
.LBB0_1273:
	s_nop 0
	v_or_b32_e32 v106, 48, v152
	v_pk_mul_f32 v[100:101], v[150:151], v[100:101]
	v_pk_mul_f32 v[96:97], v[150:151], v[96:97]
	v_ashrrev_i32_e32 v107, 31, v106
	v_pk_mul_f32 v[108:109], v[150:151], v[98:99]
	v_cvt_pk_bf16_f32 v98, v100, v101
	v_cvt_pk_bf16_f32 v100, v96, v97
	v_lshlrev_b64 v[96:97], 13, v[106:107]
	v_pk_mul_f32 v[102:103], v[150:151], v[102:103]
	v_lshl_add_u64 v[96:97], s[60:61], 0, v[96:97]
	v_cvt_pk_bf16_f32 v99, v102, v103
	v_cvt_pk_bf16_f32 v101, v108, v109
	v_lshl_add_u64 v[96:97], v[154:155], 1, v[96:97]
	global_store_dwordx4 v[96:97], v[98:101], off sc1
	s_and_b64 vcc, exec, s[6:7]
	s_nop 0
	v_add_u32_e32 v98, 0x80, v152
	v_bfe_u32 v100, v98, 6, 4
	v_cndmask_b32_e64 v99, v156, v100, s[0:1]
	v_lshlrev_b32_e32 v136, 7, v99
	s_cbranch_vccnz .LBB0_1275
.LBB0_1275:
	v_pk_mul_f32 v[92:93], v[150:151], v[92:93]
	v_pk_mul_f32 v[94:95], v[150:151], v[94:95]
	v_pk_mul_f32 v[88:89], v[150:151], v[88:89]
	v_ashrrev_i32_e32 v99, 31, v98
	v_cvt_pk_bf16_f32 v92, v92, v93
	v_cvt_pk_bf16_f32 v93, v94, v95
	v_cvt_pk_bf16_f32 v94, v88, v89
	v_lshlrev_b64 v[88:89], 13, v[98:99]
	v_pk_mul_f32 v[90:91], v[150:151], v[90:91]
	v_lshl_add_u64 v[88:89], s[60:61], 0, v[88:89]
	v_cvt_pk_bf16_f32 v95, v90, v91
	v_lshl_add_u64 v[90:91], v[154:155], 1, v[88:89]
	v_cndmask_b32_e64 v88, v159, v100, s[0:1]
	s_and_b64 vcc, exec, s[6:7]
	v_lshlrev_b32_e32 v88, 7, v88
	global_store_dwordx4 v[90:91], v[92:95], off sc1
	s_cbranch_vccnz .LBB0_1277
.LBB0_1277:
	v_pk_mul_f32 v[84:85], v[150:151], v[84:85]
	v_pk_mul_f32 v[80:81], v[150:151], v[80:81]
	v_pk_mul_f32 v[92:93], v[150:151], v[82:83]
	v_cvt_pk_bf16_f32 v82, v84, v85
	v_cvt_pk_bf16_f32 v84, v80, v81
	v_lshlrev_b64 v[80:81], 13, v[152:153]
	v_lshl_add_u64 v[80:81], s[60:61], 0, v[80:81]
	v_pk_mul_f32 v[86:87], v[150:151], v[86:87]
	v_lshl_add_u64 v[80:81], v[154:155], 1, v[80:81]
	v_cvt_pk_bf16_f32 v83, v86, v87
	v_add_co_u32_e32 v86, vcc, 0x120000, v80
	v_cvt_pk_bf16_f32 v85, v92, v93
	s_nop 0
	v_addc_co_u32_e32 v87, vcc, 0, v81, vcc
	global_store_dwordx4 v[86:87], v[82:85], off sc1
	s_and_b64 vcc, exec, s[6:7]
	s_nop 0
	v_cndmask_b32_e64 v82, v160, v100, s[0:1]
	v_lshlrev_b32_e32 v82, 7, v82
	s_cbranch_vccnz .LBB0_1279
.LBB0_1279:
	v_pk_mul_f32 v[76:77], v[150:151], v[76:77]
	v_pk_mul_f32 v[78:79], v[150:151], v[78:79]
	v_pk_mul_f32 v[84:85], v[150:151], v[72:73]
	v_pk_mul_f32 v[86:87], v[150:151], v[74:75]
	v_cvt_pk_bf16_f32 v72, v76, v77
	v_add_co_u32_e32 v76, vcc, 0x140000, v80
	v_cvt_pk_bf16_f32 v73, v78, v79
	v_cvt_pk_bf16_f32 v74, v84, v85
	v_cvt_pk_bf16_f32 v75, v86, v87
	v_addc_co_u32_e32 v77, vcc, 0, v81, vcc
	global_store_dwordx4 v[76:77], v[72:75], off sc1
	s_and_b64 vcc, exec, s[6:7]
	s_nop 0
	v_cndmask_b32_e64 v72, v161, v100, s[0:1]
	v_lshlrev_b32_e32 v72, 7, v72
	s_cbranch_vccnz .LBB0_1281
.LBB0_1281:
	v_pk_mul_f32 v[68:69], v[150:151], v[68:69]
	v_pk_mul_f32 v[64:65], v[150:151], v[64:65]
	v_pk_mul_f32 v[74:75], v[150:151], v[66:67]
	v_cvt_pk_bf16_f32 v66, v68, v69
	v_cvt_pk_bf16_f32 v68, v64, v65
	v_lshlrev_b64 v[64:65], 13, v[152:153]
	v_lshl_add_u64 v[64:65], s[60:61], 0, v[64:65]
	v_pk_mul_f32 v[70:71], v[150:151], v[70:71]
	v_lshl_add_u64 v[64:65], v[154:155], 1, v[64:65]
	v_cvt_pk_bf16_f32 v67, v70, v71
	v_add_co_u32_e32 v70, vcc, 0x160000, v64
	v_cvt_pk_bf16_f32 v69, v74, v75
	s_nop 0
	v_addc_co_u32_e32 v71, vcc, 0, v65, vcc
	s_and_b64 vcc, exec, s[6:7]
	global_store_dwordx4 v[70:71], v[66:69], off sc1
	s_cbranch_vccnz .LBB0_1283
.LBB0_1283:
	v_pk_mul_f32 v[60:61], v[150:151], v[60:61]
	v_pk_mul_f32 v[62:63], v[150:151], v[62:63]
	v_pk_mul_f32 v[66:67], v[150:151], v[56:57]
	v_pk_mul_f32 v[68:69], v[150:151], v[58:59]
	v_cvt_pk_bf16_f32 v56, v60, v61
	v_cvt_pk_bf16_f32 v57, v62, v63
	v_cvt_pk_bf16_f32 v58, v66, v67
	v_cvt_pk_bf16_f32 v59, v68, v69
	s_and_b64 vcc, exec, s[6:7]
	global_store_dwordx4 v[120:121], v[56:59], off offset:256 sc1
	s_cbranch_vccnz .LBB0_1285
.LBB0_1285:
	v_pk_mul_f32 v[52:53], v[150:151], v[52:53]
	v_pk_mul_f32 v[54:55], v[150:151], v[54:55]
	v_pk_mul_f32 v[56:57], v[150:151], v[48:49]
	v_pk_mul_f32 v[58:59], v[150:151], v[50:51]
	v_cvt_pk_bf16_f32 v48, v52, v53
	v_cvt_pk_bf16_f32 v49, v54, v55
	v_cvt_pk_bf16_f32 v50, v56, v57
	v_cvt_pk_bf16_f32 v51, v58, v59
	s_and_b64 vcc, exec, s[6:7]
	global_store_dwordx4 v[112:113], v[48:51], off offset:256 sc1
	s_cbranch_vccnz .LBB0_1287
.LBB0_1287:
	v_pk_mul_f32 v[44:45], v[150:151], v[44:45]
	v_pk_mul_f32 v[46:47], v[150:151], v[46:47]
	v_pk_mul_f32 v[48:49], v[150:151], v[40:41]
	v_pk_mul_f32 v[50:51], v[150:151], v[42:43]
	v_cvt_pk_bf16_f32 v40, v44, v45
	v_cvt_pk_bf16_f32 v41, v46, v47
	v_cvt_pk_bf16_f32 v42, v48, v49
	v_cvt_pk_bf16_f32 v43, v50, v51
	s_and_b64 vcc, exec, s[6:7]
	global_store_dwordx4 v[104:105], v[40:43], off offset:256 sc1
	s_cbranch_vccnz .LBB0_1289
.LBB0_1289:
	v_pk_mul_f32 v[36:37], v[150:151], v[36:37]
	v_pk_mul_f32 v[38:39], v[150:151], v[38:39]
	v_pk_mul_f32 v[40:41], v[150:151], v[32:33]
	v_pk_mul_f32 v[42:43], v[150:151], v[34:35]
	v_cvt_pk_bf16_f32 v32, v36, v37
	v_cvt_pk_bf16_f32 v33, v38, v39
	v_cvt_pk_bf16_f32 v34, v40, v41
	v_cvt_pk_bf16_f32 v35, v42, v43
	s_and_b64 vcc, exec, s[6:7]
	global_store_dwordx4 v[96:97], v[32:35], off offset:256 sc1
	s_cbranch_vccnz .LBB0_1291
.LBB0_1291:
	v_pk_mul_f32 v[28:29], v[150:151], v[28:29]
	v_pk_mul_f32 v[30:31], v[150:151], v[30:31]
	v_pk_mul_f32 v[32:33], v[150:151], v[24:25]
	v_pk_mul_f32 v[34:35], v[150:151], v[26:27]
	v_cvt_pk_bf16_f32 v24, v28, v29
	v_cvt_pk_bf16_f32 v25, v30, v31
	v_cvt_pk_bf16_f32 v26, v32, v33
	v_cvt_pk_bf16_f32 v27, v34, v35
	s_and_b64 vcc, exec, s[6:7]
	global_store_dwordx4 v[90:91], v[24:27], off offset:256 sc1
	s_cbranch_vccnz .LBB0_1293
.LBB0_1293:
	v_pk_mul_f32 v[20:21], v[150:151], v[20:21]
	v_pk_mul_f32 v[22:23], v[150:151], v[22:23]
	v_pk_mul_f32 v[26:27], v[150:151], v[16:17]
	v_pk_mul_f32 v[28:29], v[150:151], v[18:19]
	v_lshl_add_u64 v[24:25], v[80:81], 0, s[38:39]
	v_cvt_pk_bf16_f32 v16, v20, v21
	v_cvt_pk_bf16_f32 v17, v22, v23
	v_cvt_pk_bf16_f32 v18, v26, v27
	v_cvt_pk_bf16_f32 v19, v28, v29
	s_and_b64 vcc, exec, s[6:7]
	global_store_dwordx4 v[24:25], v[16:19], off offset:256 sc1
	s_cbranch_vccnz .LBB0_1295
.LBB0_1295:
	v_pk_mul_f32 v[12:13], v[150:151], v[12:13]
	v_pk_mul_f32 v[14:15], v[150:151], v[14:15]
	v_pk_mul_f32 v[18:19], v[150:151], v[8:9]
	v_pk_mul_f32 v[20:21], v[150:151], v[10:11]
	v_lshl_add_u64 v[16:17], v[80:81], 0, s[40:41]
	v_cvt_pk_bf16_f32 v8, v12, v13
	v_cvt_pk_bf16_f32 v9, v14, v15
	v_cvt_pk_bf16_f32 v10, v18, v19
	v_cvt_pk_bf16_f32 v11, v20, v21
	s_and_b64 vcc, exec, s[6:7]
	global_store_dwordx4 v[16:17], v[8:11], off offset:256 sc1
	s_cbranch_vccnz .LBB0_1260
	s_branch .LBB0_1260

.Lrope_1267:
	s_and_b32 s18, s54, -4
	s_cmp_eq_u32 s18, 4
	s_cselect_b64 vcc, -1, 0
	v_or_b32_e32 v152, s47, v156
	v_cndmask_b32_e32 v150, 1.0, v165, vcc
	v_pk_mul_f32 v[124:125], v[150:151], v[124:125] op_sel_hi:[0,1]
	v_pk_mul_f32 v[120:121], v[150:151], v[120:121] op_sel_hi:[0,1]
	v_ashrrev_i32_e32 v153, 31, v152
	v_lshl_or_b32 v154, s54, 8, v158
	v_pk_mul_f32 v[166:167], v[150:151], v[122:123] op_sel_hi:[0,1]
	v_cvt_pk_bf16_f32 v122, v124, v125
	v_cvt_pk_bf16_f32 v124, v120, v121
	v_lshlrev_b64 v[120:121], 13, v[152:153]
	v_ashrrev_i32_e32 v155, 31, v154
	v_pk_mul_f32 v[126:127], v[150:151], v[126:127] op_sel_hi:[0,1]
	v_lshl_add_u64 v[120:121], s[60:61], 0, v[120:121]
	v_cvt_pk_bf16_f32 v123, v126, v127
	v_cvt_pk_bf16_f32 v125, v166, v167
	v_lshl_add_u64 v[120:121], v[154:155], 1, v[120:121]
	s_and_b64 vcc, exec, s[6:7]
	global_store_dwordx4 v[120:121], v[122:125], off sc1
	s_nop 1
	s_waitcnt vmcnt(13)
	v_mov_b64_e32 v[122:123], v[186:187]
	v_mov_b64_e32 v[124:125], v[188:189]
	v_mov_b64_e32 v[166:167], v[190:191]
	v_mov_b64_e32 v[168:169], v[192:193]
	v_pk_mul_f32 v[126:127], v[116:117], v[122:123]
	v_pk_mul_f32 v[170:171], v[116:117], v[166:167] op_sel:[1,0] op_sel_hi:[0,0]
	v_pk_mul_f32 v[166:167], v[118:119], v[166:167] op_sel:[1,1] op_sel_hi:[0,1]
	v_pk_mul_f32 v[172:173], v[112:113], v[168:169] op_sel:[1,0] op_sel_hi:[0,0]
	v_mov_b32_e32 v168, v125
	v_mul_f32_e32 v136, v115, v169
	v_mul_f32_e32 v174, v115, v125
	v_pk_fma_f32 v[116:117], v[116:117], v[122:123], v[170:171] op_sel_hi:[1,0,1]
	v_pk_fma_f32 v[176:177], v[118:119], v[122:123], v[166:167] op_sel:[0,1,0] neg_lo:[0,0,1] neg_hi:[0,0,1]
	v_pk_fma_f32 v[118:119], v[118:119], v[122:123], v[166:167] op_sel:[0,1,0]
	v_pk_fma_f32 v[122:123], v[112:113], v[124:125], v[172:173] op_sel_hi:[1,0,1] neg_lo:[0,0,1] neg_hi:[0,0,1]
	v_pk_fma_f32 v[112:113], v[112:113], v[124:125], v[172:173] op_sel_hi:[1,0,1]
	v_mov_b32_e32 v124, v169
	v_pk_fma_f32 v[166:167], v[114:115], v[168:169], v[136:137] op_sel_hi:[1,1,0] neg_lo:[0,0,1] neg_hi:[0,0,1]
	v_pk_fma_f32 v[124:125], v[114:115], v[124:125], v[174:175] op_sel_hi:[1,1,0]
	v_sub_f32_e32 v116, v126, v170
	v_mov_b32_e32 v118, v176
	v_mov_b32_e32 v112, v122
	v_mov_b32_e32 v114, v166
	v_mov_b32_e32 v115, v124
.Lrope_1269:
	v_mov_b32_e32 v151, v150
	v_or_b32_e32 v122, 16, v152
	v_pk_mul_f32 v[116:117], v[150:151], v[116:117]
	v_pk_mul_f32 v[112:113], v[150:151], v[112:113]
	v_ashrrev_i32_e32 v123, 31, v122
	v_pk_mul_f32 v[124:125], v[150:151], v[114:115]
	v_cvt_pk_bf16_f32 v114, v116, v117
	v_cvt_pk_bf16_f32 v116, v112, v113
	v_lshlrev_b64 v[112:113], 13, v[122:123]
	v_pk_mul_f32 v[118:119], v[150:151], v[118:119]
	v_lshl_add_u64 v[112:113], s[60:61], 0, v[112:113]
	v_cvt_pk_bf16_f32 v115, v118, v119
	v_cvt_pk_bf16_f32 v117, v124, v125
	v_lshl_add_u64 v[112:113], v[154:155], 1, v[112:113]
	s_and_b64 vcc, exec, s[6:7]
	global_store_dwordx4 v[112:113], v[114:117], off sc1
	s_nop 1
	s_waitcnt vmcnt(12)
	v_mov_b64_e32 v[114:115], v[194:195]
	v_mov_b64_e32 v[116:117], v[196:197]
	v_mov_b64_e32 v[122:123], v[198:199]
	v_mov_b64_e32 v[124:125], v[200:201]
	v_pk_mul_f32 v[118:119], v[108:109], v[114:115]
	v_pk_mul_f32 v[126:127], v[108:109], v[122:123] op_sel:[1,0] op_sel_hi:[0,0]
	v_pk_mul_f32 v[122:123], v[110:111], v[122:123] op_sel:[1,1] op_sel_hi:[0,1]
	v_pk_mul_f32 v[166:167], v[104:105], v[124:125] op_sel:[1,0] op_sel_hi:[0,0]
	v_mov_b32_e32 v124, v117
	v_mul_f32_e32 v136, v107, v125
	v_mul_f32_e32 v168, v107, v117
	v_pk_fma_f32 v[108:109], v[108:109], v[114:115], v[126:127] op_sel_hi:[1,0,1]
	v_pk_fma_f32 v[170:171], v[110:111], v[114:115], v[122:123] op_sel:[0,1,0] neg_lo:[0,0,1] neg_hi:[0,0,1]
	v_pk_fma_f32 v[110:111], v[110:111], v[114:115], v[122:123] op_sel:[0,1,0]
	v_pk_fma_f32 v[114:115], v[104:105], v[116:117], v[166:167] op_sel_hi:[1,0,1] neg_lo:[0,0,1] neg_hi:[0,0,1]
	v_pk_fma_f32 v[104:105], v[104:105], v[116:117], v[166:167] op_sel_hi:[1,0,1]
	v_mov_b32_e32 v116, v125
	v_pk_fma_f32 v[122:123], v[106:107], v[124:125], v[136:137] op_sel_hi:[1,1,0] neg_lo:[0,0,1] neg_hi:[0,0,1]
	v_pk_fma_f32 v[116:117], v[106:107], v[116:117], v[168:169] op_sel_hi:[1,1,0]
	v_sub_f32_e32 v108, v118, v126
	v_mov_b32_e32 v110, v170
	v_mov_b32_e32 v104, v114
	v_mov_b32_e32 v106, v122
	v_mov_b32_e32 v107, v116
.Lrope_1271:
	s_nop 0
	v_or_b32_e32 v114, 32, v152
	v_pk_mul_f32 v[108:109], v[150:151], v[108:109]
	v_pk_mul_f32 v[104:105], v[150:151], v[104:105]
	v_ashrrev_i32_e32 v115, 31, v114
	v_pk_mul_f32 v[116:117], v[150:151], v[106:107]
	v_cvt_pk_bf16_f32 v106, v108, v109
	v_cvt_pk_bf16_f32 v108, v104, v105
	v_lshlrev_b64 v[104:105], 13, v[114:115]
	v_pk_mul_f32 v[110:111], v[150:151], v[110:111]
	v_lshl_add_u64 v[104:105], s[60:61], 0, v[104:105]
	v_cvt_pk_bf16_f32 v107, v110, v111
	v_cvt_pk_bf16_f32 v109, v116, v117
	v_lshl_add_u64 v[104:105], v[154:155], 1, v[104:105]
	s_and_b64 vcc, exec, s[6:7]
	global_store_dwordx4 v[104:105], v[106:109], off sc1
	s_nop 1
	s_waitcnt vmcnt(11)
	v_mov_b64_e32 v[106:107], v[202:203]
	v_mov_b64_e32 v[108:109], v[204:205]
	v_mov_b64_e32 v[114:115], v[206:207]
	v_mov_b64_e32 v[116:117], v[208:209]
	v_pk_mul_f32 v[110:111], v[100:101], v[106:107]
	v_pk_mul_f32 v[118:119], v[100:101], v[114:115] op_sel:[1,0] op_sel_hi:[0,0]
	v_pk_mul_f32 v[114:115], v[102:103], v[114:115] op_sel:[1,1] op_sel_hi:[0,1]
	v_pk_mul_f32 v[122:123], v[96:97], v[116:117] op_sel:[1,0] op_sel_hi:[0,0]
	v_mov_b32_e32 v116, v109
	v_mul_f32_e32 v124, v99, v117
	v_mul_f32_e32 v126, v99, v109
	v_pk_fma_f32 v[100:101], v[100:101], v[106:107], v[118:119] op_sel_hi:[1,0,1]
	v_pk_fma_f32 v[166:167], v[102:103], v[106:107], v[114:115] op_sel:[0,1,0] neg_lo:[0,0,1] neg_hi:[0,0,1]
	v_pk_fma_f32 v[102:103], v[102:103], v[106:107], v[114:115] op_sel:[0,1,0]
	v_pk_fma_f32 v[106:107], v[96:97], v[108:109], v[122:123] op_sel_hi:[1,0,1] neg_lo:[0,0,1] neg_hi:[0,0,1]
	v_pk_fma_f32 v[96:97], v[96:97], v[108:109], v[122:123] op_sel_hi:[1,0,1]
	v_mov_b32_e32 v108, v117
	v_pk_fma_f32 v[114:115], v[98:99], v[116:117], v[124:125] op_sel_hi:[1,1,0] neg_lo:[0,0,1] neg_hi:[0,0,1]
	v_pk_fma_f32 v[108:109], v[98:99], v[108:109], v[126:127] op_sel_hi:[1,1,0]
	v_sub_f32_e32 v100, v110, v118
	v_mov_b32_e32 v102, v166
	v_mov_b32_e32 v96, v106
	v_mov_b32_e32 v98, v114
	v_mov_b32_e32 v99, v108
.Lrope_1273:
	s_nop 0
	v_or_b32_e32 v106, 48, v152
	v_pk_mul_f32 v[100:101], v[150:151], v[100:101]
	v_pk_mul_f32 v[96:97], v[150:151], v[96:97]
	v_ashrrev_i32_e32 v107, 31, v106
	v_pk_mul_f32 v[108:109], v[150:151], v[98:99]
	v_cvt_pk_bf16_f32 v98, v100, v101
	v_cvt_pk_bf16_f32 v100, v96, v97
	v_lshlrev_b64 v[96:97], 13, v[106:107]
	v_pk_mul_f32 v[102:103], v[150:151], v[102:103]
	v_lshl_add_u64 v[96:97], s[60:61], 0, v[96:97]
	v_cvt_pk_bf16_f32 v99, v102, v103
	v_cvt_pk_bf16_f32 v101, v108, v109
	v_lshl_add_u64 v[96:97], v[154:155], 1, v[96:97]
	global_store_dwordx4 v[96:97], v[98:101], off sc1
	s_and_b64 vcc, exec, s[6:7]
	s_nop 0
	v_add_u32_e32 v98, 0x80, v152
	v_bfe_u32 v100, v98, 6, 4
	v_cndmask_b32_e64 v99, v156, v100, s[0:1]
	v_lshlrev_b32_e32 v136, 7, v99
	s_nop 1
	s_waitcnt vmcnt(10)
	v_mov_b64_e32 v[106:107], v[210:211]
	v_mov_b64_e32 v[108:109], v[212:213]
	v_mov_b64_e32 v[114:115], v[214:215]
	v_mov_b64_e32 v[116:117], v[216:217]
	v_pk_mul_f32 v[102:103], v[92:93], v[106:107]
	v_pk_mul_f32 v[110:111], v[92:93], v[114:115] op_sel:[1,0] op_sel_hi:[0,0]
	v_pk_mul_f32 v[114:115], v[94:95], v[114:115] op_sel:[1,1] op_sel_hi:[0,1]
	v_pk_mul_f32 v[118:119], v[88:89], v[116:117] op_sel:[1,0] op_sel_hi:[0,0]
	v_mov_b32_e32 v116, v109
	v_mul_f32_e32 v122, v91, v117
	v_mul_f32_e32 v124, v91, v109
	v_pk_fma_f32 v[92:93], v[92:93], v[106:107], v[110:111] op_sel_hi:[1,0,1]
	v_pk_fma_f32 v[126:127], v[94:95], v[106:107], v[114:115] op_sel:[0,1,0] neg_lo:[0,0,1] neg_hi:[0,0,1]
	v_pk_fma_f32 v[94:95], v[94:95], v[106:107], v[114:115] op_sel:[0,1,0]
	v_pk_fma_f32 v[106:107], v[88:89], v[108:109], v[118:119] op_sel_hi:[1,0,1] neg_lo:[0,0,1] neg_hi:[0,0,1]
	v_pk_fma_f32 v[88:89], v[88:89], v[108:109], v[118:119] op_sel_hi:[1,0,1]
	v_mov_b32_e32 v108, v117
	v_pk_fma_f32 v[114:115], v[90:91], v[116:117], v[122:123] op_sel_hi:[1,1,0] neg_lo:[0,0,1] neg_hi:[0,0,1]
	v_pk_fma_f32 v[108:109], v[90:91], v[108:109], v[124:125] op_sel_hi:[1,1,0]
	v_sub_f32_e32 v92, v102, v110
	v_mov_b32_e32 v94, v126
	v_mov_b32_e32 v88, v106
	v_mov_b32_e32 v90, v114
	v_mov_b32_e32 v91, v108
.Lrope_1275:
	v_pk_mul_f32 v[92:93], v[150:151], v[92:93]
	v_pk_mul_f32 v[94:95], v[150:151], v[94:95]
	v_pk_mul_f32 v[88:89], v[150:151], v[88:89]
	v_ashrrev_i32_e32 v99, 31, v98
	v_cvt_pk_bf16_f32 v92, v92, v93
	v_cvt_pk_bf16_f32 v93, v94, v95
	v_cvt_pk_bf16_f32 v94, v88, v89
	v_lshlrev_b64 v[88:89], 13, v[98:99]
	v_pk_mul_f32 v[90:91], v[150:151], v[90:91]
	v_lshl_add_u64 v[88:89], s[60:61], 0, v[88:89]
	v_cvt_pk_bf16_f32 v95, v90, v91
	v_lshl_add_u64 v[90:91], v[154:155], 1, v[88:89]
	v_cndmask_b32_e64 v88, v159, v100, s[0:1]
	s_and_b64 vcc, exec, s[6:7]
	v_lshlrev_b32_e32 v88, 7, v88
	global_store_dwordx4 v[90:91], v[92:95], off sc1
	s_nop 1
	s_waitcnt vmcnt(9)
	v_mov_b64_e32 v[92:93], v[218:219]
	v_mov_b64_e32 v[94:95], v[220:221]
	v_mov_b64_e32 v[106:107], v[226:227]
	v_mov_b64_e32 v[108:109], v[228:229]
	v_pk_mul_f32 v[98:99], v[84:85], v[92:93]
	v_pk_mul_f32 v[102:103], v[84:85], v[106:107] op_sel:[1,0] op_sel_hi:[0,0]
	v_pk_mul_f32 v[106:107], v[86:87], v[106:107] op_sel:[1,1] op_sel_hi:[0,1]
	v_pk_mul_f32 v[110:111], v[80:81], v[108:109] op_sel:[1,0] op_sel_hi:[0,0]
	v_mov_b32_e32 v108, v95
	v_mul_f32_e32 v114, v83, v109
	v_mul_f32_e32 v116, v83, v95
	v_pk_fma_f32 v[84:85], v[84:85], v[92:93], v[102:103] op_sel_hi:[1,0,1]
	v_pk_fma_f32 v[118:119], v[86:87], v[92:93], v[106:107] op_sel:[0,1,0] neg_lo:[0,0,1] neg_hi:[0,0,1]
	v_pk_fma_f32 v[86:87], v[86:87], v[92:93], v[106:107] op_sel:[0,1,0]
	v_pk_fma_f32 v[92:93], v[80:81], v[94:95], v[110:111] op_sel_hi:[1,0,1] neg_lo:[0,0,1] neg_hi:[0,0,1]
	v_pk_fma_f32 v[80:81], v[80:81], v[94:95], v[110:111] op_sel_hi:[1,0,1]
	v_mov_b32_e32 v94, v109
	v_pk_fma_f32 v[106:107], v[82:83], v[108:109], v[114:115] op_sel_hi:[1,1,0] neg_lo:[0,0,1] neg_hi:[0,0,1]
	v_pk_fma_f32 v[94:95], v[82:83], v[94:95], v[116:117] op_sel_hi:[1,1,0]
	v_sub_f32_e32 v84, v98, v102
	v_mov_b32_e32 v86, v118
	v_mov_b32_e32 v80, v92
	v_mov_b32_e32 v82, v106
	v_mov_b32_e32 v83, v94
.Lrope_1277:
	v_pk_mul_f32 v[84:85], v[150:151], v[84:85]
	v_pk_mul_f32 v[80:81], v[150:151], v[80:81]
	v_pk_mul_f32 v[92:93], v[150:151], v[82:83]
	v_cvt_pk_bf16_f32 v82, v84, v85
	v_cvt_pk_bf16_f32 v84, v80, v81
	v_lshlrev_b64 v[80:81], 13, v[152:153]
	v_lshl_add_u64 v[80:81], s[60:61], 0, v[80:81]
	v_pk_mul_f32 v[86:87], v[150:151], v[86:87]
	v_lshl_add_u64 v[80:81], v[154:155], 1, v[80:81]
	v_cvt_pk_bf16_f32 v83, v86, v87
	v_add_co_u32_e32 v86, vcc, 0x120000, v80
	v_cvt_pk_bf16_f32 v85, v92, v93
	s_nop 0
	v_addc_co_u32_e32 v87, vcc, 0, v81, vcc
	global_store_dwordx4 v[86:87], v[82:85], off sc1
	s_and_b64 vcc, exec, s[6:7]
	s_nop 0
	v_cndmask_b32_e64 v82, v160, v100, s[0:1]
	v_lshlrev_b32_e32 v82, 7, v82
	s_nop 1
	s_waitcnt vmcnt(8)
	v_mov_b64_e32 v[84:85], v[234:235]
	v_mov_b64_e32 v[86:87], v[236:237]
	v_mov_b64_e32 v[92:93], v[238:239]
	v_mov_b64_e32 v[94:95], v[240:241]
	v_pk_mul_f32 v[98:99], v[76:77], v[84:85]
	v_pk_mul_f32 v[102:103], v[76:77], v[92:93] op_sel:[1,0] op_sel_hi:[0,0]
	v_pk_mul_f32 v[92:93], v[78:79], v[92:93] op_sel:[1,1] op_sel_hi:[0,1]
	v_pk_mul_f32 v[106:107], v[72:73], v[94:95] op_sel:[1,0] op_sel_hi:[0,0]
	v_mov_b32_e32 v94, v87
	v_mul_f32_e32 v108, v75, v95
	v_mul_f32_e32 v110, v75, v87
	v_pk_fma_f32 v[76:77], v[76:77], v[84:85], v[102:103] op_sel_hi:[1,0,1]
	v_pk_fma_f32 v[114:115], v[78:79], v[84:85], v[92:93] op_sel:[0,1,0] neg_lo:[0,0,1] neg_hi:[0,0,1]
	v_pk_fma_f32 v[78:79], v[78:79], v[84:85], v[92:93] op_sel:[0,1,0]
	v_pk_fma_f32 v[84:85], v[72:73], v[86:87], v[106:107] op_sel_hi:[1,0,1] neg_lo:[0,0,1] neg_hi:[0,0,1]
	v_pk_fma_f32 v[72:73], v[72:73], v[86:87], v[106:107] op_sel_hi:[1,0,1]
	v_mov_b32_e32 v86, v95
	v_pk_fma_f32 v[92:93], v[74:75], v[94:95], v[108:109] op_sel_hi:[1,1,0] neg_lo:[0,0,1] neg_hi:[0,0,1]
	v_pk_fma_f32 v[86:87], v[74:75], v[86:87], v[110:111] op_sel_hi:[1,1,0]
	v_sub_f32_e32 v76, v98, v102
	v_mov_b32_e32 v78, v114
	v_mov_b32_e32 v72, v84
	v_mov_b32_e32 v74, v92
	v_mov_b32_e32 v75, v86
.Lrope_1279:
	v_pk_mul_f32 v[76:77], v[150:151], v[76:77]
	v_pk_mul_f32 v[78:79], v[150:151], v[78:79]
	v_pk_mul_f32 v[84:85], v[150:151], v[72:73]
	v_pk_mul_f32 v[86:87], v[150:151], v[74:75]
	v_cvt_pk_bf16_f32 v72, v76, v77
	v_add_co_u32_e32 v76, vcc, 0x140000, v80
	v_cvt_pk_bf16_f32 v73, v78, v79
	v_cvt_pk_bf16_f32 v74, v84, v85
	v_cvt_pk_bf16_f32 v75, v86, v87
	v_addc_co_u32_e32 v77, vcc, 0, v81, vcc
	global_store_dwordx4 v[76:77], v[72:75], off sc1
	s_and_b64 vcc, exec, s[6:7]
	s_nop 0
	v_cndmask_b32_e64 v72, v161, v100, s[0:1]
	v_lshlrev_b32_e32 v72, 7, v72
	s_nop 1
	s_waitcnt vmcnt(7)
	v_mov_b64_e32 v[74:75], v[242:243]
	v_mov_b64_e32 v[76:77], v[244:245]
	v_mov_b64_e32 v[84:85], v[246:247]
	v_mov_b64_e32 v[86:87], v[248:249]
	v_pk_mul_f32 v[78:79], v[68:69], v[74:75]
	v_pk_mul_f32 v[92:93], v[68:69], v[84:85] op_sel:[1,0] op_sel_hi:[0,0]
	v_pk_mul_f32 v[84:85], v[70:71], v[84:85] op_sel:[1,1] op_sel_hi:[0,1]
	v_pk_mul_f32 v[94:95], v[64:65], v[86:87] op_sel:[1,0] op_sel_hi:[0,0]
	v_mov_b32_e32 v86, v77
	v_mul_f32_e32 v98, v67, v87
	v_mul_f32_e32 v100, v67, v77
	v_pk_fma_f32 v[68:69], v[68:69], v[74:75], v[92:93] op_sel_hi:[1,0,1]
	v_pk_fma_f32 v[102:103], v[70:71], v[74:75], v[84:85] op_sel:[0,1,0] neg_lo:[0,0,1] neg_hi:[0,0,1]
	v_pk_fma_f32 v[70:71], v[70:71], v[74:75], v[84:85] op_sel:[0,1,0]
	v_pk_fma_f32 v[74:75], v[64:65], v[76:77], v[94:95] op_sel_hi:[1,0,1] neg_lo:[0,0,1] neg_hi:[0,0,1]
	v_pk_fma_f32 v[64:65], v[64:65], v[76:77], v[94:95] op_sel_hi:[1,0,1]
	v_mov_b32_e32 v76, v87
	v_pk_fma_f32 v[84:85], v[66:67], v[86:87], v[98:99] op_sel_hi:[1,1,0] neg_lo:[0,0,1] neg_hi:[0,0,1]
	v_pk_fma_f32 v[76:77], v[66:67], v[76:77], v[100:101] op_sel_hi:[1,1,0]
	v_sub_f32_e32 v68, v78, v92
	v_mov_b32_e32 v70, v102
	v_mov_b32_e32 v64, v74
	v_mov_b32_e32 v66, v84
	v_mov_b32_e32 v67, v76
.Lrope_1281:
	v_pk_mul_f32 v[68:69], v[150:151], v[68:69]
	v_pk_mul_f32 v[64:65], v[150:151], v[64:65]
	v_pk_mul_f32 v[74:75], v[150:151], v[66:67]
	v_cvt_pk_bf16_f32 v66, v68, v69
	v_cvt_pk_bf16_f32 v68, v64, v65
	v_lshlrev_b64 v[64:65], 13, v[152:153]
	v_lshl_add_u64 v[64:65], s[60:61], 0, v[64:65]
	v_pk_mul_f32 v[70:71], v[150:151], v[70:71]
	v_lshl_add_u64 v[64:65], v[154:155], 1, v[64:65]
	v_cvt_pk_bf16_f32 v67, v70, v71
	v_add_co_u32_e32 v70, vcc, 0x160000, v64
	v_cvt_pk_bf16_f32 v69, v74, v75
	s_nop 0
	v_addc_co_u32_e32 v71, vcc, 0, v65, vcc
	s_and_b64 vcc, exec, s[6:7]
	global_store_dwordx4 v[70:71], v[66:69], off sc1
	s_nop 1
	v_mov_b64_e32 v[66:67], v[178:179]
	v_mov_b64_e32 v[68:69], v[180:181]
	v_mov_b64_e32 v[74:75], v[182:183]
	v_mov_b64_e32 v[76:77], v[184:185]
	v_pk_mul_f32 v[70:71], v[60:61], v[66:67]
	v_pk_mul_f32 v[78:79], v[60:61], v[74:75] op_sel:[1,0] op_sel_hi:[0,0]
	v_pk_mul_f32 v[74:75], v[62:63], v[74:75] op_sel:[1,1] op_sel_hi:[0,1]
	v_pk_mul_f32 v[84:85], v[56:57], v[76:77] op_sel:[1,0] op_sel_hi:[0,0]
	v_mov_b32_e32 v76, v69
	v_mul_f32_e32 v86, v59, v77
	v_mul_f32_e32 v92, v59, v69
	v_pk_fma_f32 v[60:61], v[60:61], v[66:67], v[78:79] op_sel_hi:[1,0,1]
	v_pk_fma_f32 v[94:95], v[62:63], v[66:67], v[74:75] op_sel:[0,1,0] neg_lo:[0,0,1] neg_hi:[0,0,1]
	v_pk_fma_f32 v[62:63], v[62:63], v[66:67], v[74:75] op_sel:[0,1,0]
	v_pk_fma_f32 v[66:67], v[56:57], v[68:69], v[84:85] op_sel_hi:[1,0,1] neg_lo:[0,0,1] neg_hi:[0,0,1]
	v_pk_fma_f32 v[56:57], v[56:57], v[68:69], v[84:85] op_sel_hi:[1,0,1]
	v_mov_b32_e32 v68, v77
	v_pk_fma_f32 v[74:75], v[58:59], v[76:77], v[86:87] op_sel_hi:[1,1,0] neg_lo:[0,0,1] neg_hi:[0,0,1]
	v_pk_fma_f32 v[68:69], v[58:59], v[68:69], v[92:93] op_sel_hi:[1,1,0]
	v_sub_f32_e32 v60, v70, v78
	v_mov_b32_e32 v62, v94
	v_mov_b32_e32 v56, v66
	v_mov_b32_e32 v58, v74
	v_mov_b32_e32 v59, v68
.Lrope_1283:
	v_pk_mul_f32 v[60:61], v[150:151], v[60:61]
	v_pk_mul_f32 v[62:63], v[150:151], v[62:63]
	v_pk_mul_f32 v[66:67], v[150:151], v[56:57]
	v_pk_mul_f32 v[68:69], v[150:151], v[58:59]
	v_cvt_pk_bf16_f32 v56, v60, v61
	v_cvt_pk_bf16_f32 v57, v62, v63
	v_cvt_pk_bf16_f32 v58, v66, v67
	v_cvt_pk_bf16_f32 v59, v68, v69
	s_and_b64 vcc, exec, s[6:7]
	global_store_dwordx4 v[120:121], v[56:59], off offset:256 sc1
	s_nop 1
	v_mov_b64_e32 v[56:57], v[186:187]
	v_mov_b64_e32 v[58:59], v[188:189]
	v_mov_b64_e32 v[60:61], v[190:191]
	v_mov_b64_e32 v[62:63], v[192:193]
	v_pk_mul_f32 v[66:67], v[52:53], v[56:57]
	v_pk_mul_f32 v[68:69], v[52:53], v[60:61] op_sel:[1,0] op_sel_hi:[0,0]
	v_pk_mul_f32 v[60:61], v[54:55], v[60:61] op_sel:[1,1] op_sel_hi:[0,1]
	v_pk_mul_f32 v[70:71], v[48:49], v[62:63] op_sel:[1,0] op_sel_hi:[0,0]
	v_mov_b32_e32 v62, v59
	v_mul_f32_e32 v74, v51, v63
	v_mul_f32_e32 v76, v51, v59
	v_pk_fma_f32 v[52:53], v[52:53], v[56:57], v[68:69] op_sel_hi:[1,0,1]
	v_pk_fma_f32 v[78:79], v[54:55], v[56:57], v[60:61] op_sel:[0,1,0] neg_lo:[0,0,1] neg_hi:[0,0,1]
	v_pk_fma_f32 v[54:55], v[54:55], v[56:57], v[60:61] op_sel:[0,1,0]
	v_pk_fma_f32 v[56:57], v[48:49], v[58:59], v[70:71] op_sel_hi:[1,0,1] neg_lo:[0,0,1] neg_hi:[0,0,1]
	v_pk_fma_f32 v[48:49], v[48:49], v[58:59], v[70:71] op_sel_hi:[1,0,1]
	v_mov_b32_e32 v58, v63
	v_pk_fma_f32 v[60:61], v[50:51], v[62:63], v[74:75] op_sel_hi:[1,1,0] neg_lo:[0,0,1] neg_hi:[0,0,1]
	v_pk_fma_f32 v[58:59], v[50:51], v[58:59], v[76:77] op_sel_hi:[1,1,0]
	v_sub_f32_e32 v52, v66, v68
	v_mov_b32_e32 v54, v78
	v_mov_b32_e32 v48, v56
	v_mov_b32_e32 v50, v60
	v_mov_b32_e32 v51, v58
.Lrope_1285:
	v_pk_mul_f32 v[52:53], v[150:151], v[52:53]
	v_pk_mul_f32 v[54:55], v[150:151], v[54:55]
	v_pk_mul_f32 v[56:57], v[150:151], v[48:49]
	v_pk_mul_f32 v[58:59], v[150:151], v[50:51]
	v_cvt_pk_bf16_f32 v48, v52, v53
	v_cvt_pk_bf16_f32 v49, v54, v55
	v_cvt_pk_bf16_f32 v50, v56, v57
	v_cvt_pk_bf16_f32 v51, v58, v59
	s_and_b64 vcc, exec, s[6:7]
	global_store_dwordx4 v[112:113], v[48:51], off offset:256 sc1
	s_nop 1
	v_mov_b64_e32 v[48:49], v[194:195]
	v_mov_b64_e32 v[50:51], v[196:197]
	v_mov_b64_e32 v[52:53], v[198:199]
	v_mov_b64_e32 v[54:55], v[200:201]
	v_pk_mul_f32 v[56:57], v[44:45], v[48:49]
	v_pk_mul_f32 v[58:59], v[44:45], v[52:53] op_sel:[1,0] op_sel_hi:[0,0]
	v_pk_mul_f32 v[52:53], v[46:47], v[52:53] op_sel:[1,1] op_sel_hi:[0,1]
	v_pk_mul_f32 v[60:61], v[40:41], v[54:55] op_sel:[1,0] op_sel_hi:[0,0]
	v_mov_b32_e32 v54, v51
	v_mul_f32_e32 v62, v43, v55
	v_mul_f32_e32 v66, v43, v51
	v_pk_fma_f32 v[44:45], v[44:45], v[48:49], v[58:59] op_sel_hi:[1,0,1]
	v_pk_fma_f32 v[68:69], v[46:47], v[48:49], v[52:53] op_sel:[0,1,0] neg_lo:[0,0,1] neg_hi:[0,0,1]
	v_pk_fma_f32 v[46:47], v[46:47], v[48:49], v[52:53] op_sel:[0,1,0]
	v_pk_fma_f32 v[48:49], v[40:41], v[50:51], v[60:61] op_sel_hi:[1,0,1] neg_lo:[0,0,1] neg_hi:[0,0,1]
	v_pk_fma_f32 v[40:41], v[40:41], v[50:51], v[60:61] op_sel_hi:[1,0,1]
	v_mov_b32_e32 v50, v55
	v_pk_fma_f32 v[52:53], v[42:43], v[54:55], v[62:63] op_sel_hi:[1,1,0] neg_lo:[0,0,1] neg_hi:[0,0,1]
	v_pk_fma_f32 v[50:51], v[42:43], v[50:51], v[66:67] op_sel_hi:[1,1,0]
	v_sub_f32_e32 v44, v56, v58
	v_mov_b32_e32 v46, v68
	v_mov_b32_e32 v40, v48
	v_mov_b32_e32 v42, v52
	v_mov_b32_e32 v43, v50
.Lrope_1287:
	v_pk_mul_f32 v[44:45], v[150:151], v[44:45]
	v_pk_mul_f32 v[46:47], v[150:151], v[46:47]
	v_pk_mul_f32 v[48:49], v[150:151], v[40:41]
	v_pk_mul_f32 v[50:51], v[150:151], v[42:43]
	v_cvt_pk_bf16_f32 v40, v44, v45
	v_cvt_pk_bf16_f32 v41, v46, v47
	v_cvt_pk_bf16_f32 v42, v48, v49
	v_cvt_pk_bf16_f32 v43, v50, v51
	s_and_b64 vcc, exec, s[6:7]
	global_store_dwordx4 v[104:105], v[40:43], off offset:256 sc1
	s_nop 1
	v_mov_b64_e32 v[40:41], v[202:203]
	v_mov_b64_e32 v[42:43], v[204:205]
	v_mov_b64_e32 v[44:45], v[206:207]
	v_mov_b64_e32 v[46:47], v[208:209]
	v_pk_mul_f32 v[48:49], v[36:37], v[40:41]
	v_pk_mul_f32 v[50:51], v[36:37], v[44:45] op_sel:[1,0] op_sel_hi:[0,0]
	v_pk_mul_f32 v[44:45], v[38:39], v[44:45] op_sel:[1,1] op_sel_hi:[0,1]
	v_pk_mul_f32 v[52:53], v[32:33], v[46:47] op_sel:[1,0] op_sel_hi:[0,0]
	v_mov_b32_e32 v46, v43
	v_mul_f32_e32 v54, v35, v47
	v_mul_f32_e32 v56, v35, v43
	v_pk_fma_f32 v[36:37], v[36:37], v[40:41], v[50:51] op_sel_hi:[1,0,1]
	v_pk_fma_f32 v[58:59], v[38:39], v[40:41], v[44:45] op_sel:[0,1,0] neg_lo:[0,0,1] neg_hi:[0,0,1]
	v_pk_fma_f32 v[38:39], v[38:39], v[40:41], v[44:45] op_sel:[0,1,0]
	v_pk_fma_f32 v[40:41], v[32:33], v[42:43], v[52:53] op_sel_hi:[1,0,1] neg_lo:[0,0,1] neg_hi:[0,0,1]
	v_pk_fma_f32 v[32:33], v[32:33], v[42:43], v[52:53] op_sel_hi:[1,0,1]
	v_mov_b32_e32 v42, v47
	v_pk_fma_f32 v[44:45], v[34:35], v[46:47], v[54:55] op_sel_hi:[1,1,0] neg_lo:[0,0,1] neg_hi:[0,0,1]
	v_pk_fma_f32 v[42:43], v[34:35], v[42:43], v[56:57] op_sel_hi:[1,1,0]
	v_sub_f32_e32 v36, v48, v50
	v_mov_b32_e32 v38, v58
	v_mov_b32_e32 v32, v40
	v_mov_b32_e32 v34, v44
	v_mov_b32_e32 v35, v42
.Lrope_1289:
	v_pk_mul_f32 v[36:37], v[150:151], v[36:37]
	v_pk_mul_f32 v[38:39], v[150:151], v[38:39]
	v_pk_mul_f32 v[40:41], v[150:151], v[32:33]
	v_pk_mul_f32 v[42:43], v[150:151], v[34:35]
	v_cvt_pk_bf16_f32 v32, v36, v37
	v_cvt_pk_bf16_f32 v33, v38, v39
	v_cvt_pk_bf16_f32 v34, v40, v41
	v_cvt_pk_bf16_f32 v35, v42, v43
	s_and_b64 vcc, exec, s[6:7]
	global_store_dwordx4 v[96:97], v[32:35], off offset:256 sc1
	s_nop 1
	v_mov_b64_e32 v[32:33], v[210:211]
	v_mov_b64_e32 v[34:35], v[212:213]
	v_mov_b64_e32 v[36:37], v[214:215]
	v_mov_b64_e32 v[38:39], v[216:217]
	v_pk_mul_f32 v[40:41], v[28:29], v[32:33]
	v_pk_mul_f32 v[42:43], v[28:29], v[36:37] op_sel:[1,0] op_sel_hi:[0,0]
	v_pk_mul_f32 v[36:37], v[30:31], v[36:37] op_sel:[1,1] op_sel_hi:[0,1]
	v_pk_mul_f32 v[44:45], v[24:25], v[38:39] op_sel:[1,0] op_sel_hi:[0,0]
	v_mov_b32_e32 v38, v35
	v_mul_f32_e32 v46, v27, v39
	v_mul_f32_e32 v48, v27, v35
	v_pk_fma_f32 v[28:29], v[28:29], v[32:33], v[42:43] op_sel_hi:[1,0,1]
	v_pk_fma_f32 v[50:51], v[30:31], v[32:33], v[36:37] op_sel:[0,1,0] neg_lo:[0,0,1] neg_hi:[0,0,1]
	v_pk_fma_f32 v[30:31], v[30:31], v[32:33], v[36:37] op_sel:[0,1,0]
	v_pk_fma_f32 v[32:33], v[24:25], v[34:35], v[44:45] op_sel_hi:[1,0,1] neg_lo:[0,0,1] neg_hi:[0,0,1]
	v_pk_fma_f32 v[24:25], v[24:25], v[34:35], v[44:45] op_sel_hi:[1,0,1]
	v_mov_b32_e32 v34, v39
	v_pk_fma_f32 v[36:37], v[26:27], v[38:39], v[46:47] op_sel_hi:[1,1,0] neg_lo:[0,0,1] neg_hi:[0,0,1]
	v_pk_fma_f32 v[34:35], v[26:27], v[34:35], v[48:49] op_sel_hi:[1,1,0]
	v_sub_f32_e32 v28, v40, v42
	v_mov_b32_e32 v30, v50
	v_mov_b32_e32 v24, v32
	v_mov_b32_e32 v26, v36
	v_mov_b32_e32 v27, v34
.Lrope_1291:
	v_pk_mul_f32 v[28:29], v[150:151], v[28:29]
	v_pk_mul_f32 v[30:31], v[150:151], v[30:31]
	v_pk_mul_f32 v[32:33], v[150:151], v[24:25]
	v_pk_mul_f32 v[34:35], v[150:151], v[26:27]
	v_cvt_pk_bf16_f32 v24, v28, v29
	v_cvt_pk_bf16_f32 v25, v30, v31
	v_cvt_pk_bf16_f32 v26, v32, v33
	v_cvt_pk_bf16_f32 v27, v34, v35
	s_and_b64 vcc, exec, s[6:7]
	global_store_dwordx4 v[90:91], v[24:27], off offset:256 sc1
	s_nop 1
	v_mov_b64_e32 v[24:25], v[218:219]
	v_mov_b64_e32 v[26:27], v[220:221]
	v_mov_b64_e32 v[28:29], v[226:227]
	v_mov_b64_e32 v[30:31], v[228:229]
	v_pk_mul_f32 v[32:33], v[20:21], v[24:25]
	v_pk_mul_f32 v[34:35], v[20:21], v[28:29] op_sel:[1,0] op_sel_hi:[0,0]
	v_pk_mul_f32 v[28:29], v[22:23], v[28:29] op_sel:[1,1] op_sel_hi:[0,1]
	v_pk_mul_f32 v[36:37], v[16:17], v[30:31] op_sel:[1,0] op_sel_hi:[0,0]
	v_mov_b32_e32 v30, v27
	v_mul_f32_e32 v38, v19, v31
	v_mul_f32_e32 v40, v19, v27
	v_pk_fma_f32 v[20:21], v[20:21], v[24:25], v[34:35] op_sel_hi:[1,0,1]
	v_pk_fma_f32 v[42:43], v[22:23], v[24:25], v[28:29] op_sel:[0,1,0] neg_lo:[0,0,1] neg_hi:[0,0,1]
	v_pk_fma_f32 v[22:23], v[22:23], v[24:25], v[28:29] op_sel:[0,1,0]
	v_pk_fma_f32 v[24:25], v[16:17], v[26:27], v[36:37] op_sel_hi:[1,0,1] neg_lo:[0,0,1] neg_hi:[0,0,1]
	v_pk_fma_f32 v[16:17], v[16:17], v[26:27], v[36:37] op_sel_hi:[1,0,1]
	v_mov_b32_e32 v26, v31
	v_pk_fma_f32 v[28:29], v[18:19], v[30:31], v[38:39] op_sel_hi:[1,1,0] neg_lo:[0,0,1] neg_hi:[0,0,1]
	v_pk_fma_f32 v[26:27], v[18:19], v[26:27], v[40:41] op_sel_hi:[1,1,0]
	v_sub_f32_e32 v20, v32, v34
	v_mov_b32_e32 v22, v42
	v_mov_b32_e32 v16, v24
	v_mov_b32_e32 v18, v28
	v_mov_b32_e32 v19, v26
.Lrope_1293:
	v_pk_mul_f32 v[20:21], v[150:151], v[20:21]
	v_pk_mul_f32 v[22:23], v[150:151], v[22:23]
	v_pk_mul_f32 v[26:27], v[150:151], v[16:17]
	v_pk_mul_f32 v[28:29], v[150:151], v[18:19]
	v_lshl_add_u64 v[24:25], v[80:81], 0, s[38:39]
	v_cvt_pk_bf16_f32 v16, v20, v21
	v_cvt_pk_bf16_f32 v17, v22, v23
	v_cvt_pk_bf16_f32 v18, v26, v27
	v_cvt_pk_bf16_f32 v19, v28, v29
	s_and_b64 vcc, exec, s[6:7]
	global_store_dwordx4 v[24:25], v[16:19], off offset:256 sc1
	s_nop 1
	v_mov_b64_e32 v[16:17], v[234:235]
	v_mov_b64_e32 v[18:19], v[236:237]
	v_mov_b64_e32 v[20:21], v[238:239]
	v_mov_b64_e32 v[22:23], v[240:241]
	v_pk_mul_f32 v[24:25], v[12:13], v[16:17]
	v_pk_mul_f32 v[26:27], v[12:13], v[20:21] op_sel:[1,0] op_sel_hi:[0,0]
	v_pk_mul_f32 v[20:21], v[14:15], v[20:21] op_sel:[1,1] op_sel_hi:[0,1]
	v_pk_mul_f32 v[28:29], v[8:9], v[22:23] op_sel:[1,0] op_sel_hi:[0,0]
	v_mov_b32_e32 v22, v19
	v_mul_f32_e32 v30, v11, v23
	v_mul_f32_e32 v32, v11, v19
	v_pk_fma_f32 v[12:13], v[12:13], v[16:17], v[26:27] op_sel_hi:[1,0,1]
	v_pk_fma_f32 v[34:35], v[14:15], v[16:17], v[20:21] op_sel:[0,1,0] neg_lo:[0,0,1] neg_hi:[0,0,1]
	v_pk_fma_f32 v[14:15], v[14:15], v[16:17], v[20:21] op_sel:[0,1,0]
	v_pk_fma_f32 v[16:17], v[8:9], v[18:19], v[28:29] op_sel_hi:[1,0,1] neg_lo:[0,0,1] neg_hi:[0,0,1]
	v_pk_fma_f32 v[8:9], v[8:9], v[18:19], v[28:29] op_sel_hi:[1,0,1]
	v_mov_b32_e32 v18, v23
	v_pk_fma_f32 v[20:21], v[10:11], v[22:23], v[30:31] op_sel_hi:[1,1,0] neg_lo:[0,0,1] neg_hi:[0,0,1]
	v_pk_fma_f32 v[18:19], v[10:11], v[18:19], v[32:33] op_sel_hi:[1,1,0]
	v_sub_f32_e32 v12, v24, v26
	v_mov_b32_e32 v14, v34
	v_mov_b32_e32 v8, v16
	v_mov_b32_e32 v10, v20
	v_mov_b32_e32 v11, v18
.Lrope_1295:
	v_pk_mul_f32 v[12:13], v[150:151], v[12:13]
	v_pk_mul_f32 v[14:15], v[150:151], v[14:15]
	v_pk_mul_f32 v[18:19], v[150:151], v[8:9]
	v_pk_mul_f32 v[20:21], v[150:151], v[10:11]
	v_lshl_add_u64 v[16:17], v[80:81], 0, s[40:41]
	v_cvt_pk_bf16_f32 v8, v12, v13
	v_cvt_pk_bf16_f32 v9, v14, v15
	v_cvt_pk_bf16_f32 v10, v18, v19
	v_cvt_pk_bf16_f32 v11, v20, v21
	s_and_b64 vcc, exec, s[6:7]
	global_store_dwordx4 v[16:17], v[8:11], off offset:256 sc1
	s_nop 1
	v_mov_b64_e32 v[8:9], v[242:243]
	v_mov_b64_e32 v[10:11], v[244:245]
	v_mov_b64_e32 v[12:13], v[246:247]
	v_mov_b64_e32 v[14:15], v[248:249]
	v_pk_mul_f32 v[16:17], v[4:5], v[8:9]
	v_pk_mul_f32 v[18:19], v[4:5], v[12:13] op_sel:[1,0] op_sel_hi:[0,0]
	v_pk_mul_f32 v[12:13], v[6:7], v[12:13] op_sel:[1,1] op_sel_hi:[0,1]
	v_pk_mul_f32 v[20:21], v[0:1], v[14:15] op_sel:[1,0] op_sel_hi:[0,0]
	v_mov_b32_e32 v14, v11
	v_mul_f32_e32 v22, v3, v15
	v_mul_f32_e32 v24, v3, v11
	v_pk_fma_f32 v[4:5], v[4:5], v[8:9], v[18:19] op_sel_hi:[1,0,1]
	v_pk_fma_f32 v[26:27], v[6:7], v[8:9], v[12:13] op_sel:[0,1,0] neg_lo:[0,0,1] neg_hi:[0,0,1]
	v_pk_fma_f32 v[6:7], v[6:7], v[8:9], v[12:13] op_sel:[0,1,0]
	v_pk_fma_f32 v[8:9], v[0:1], v[10:11], v[20:21] op_sel_hi:[1,0,1] neg_lo:[0,0,1] neg_hi:[0,0,1]
	v_pk_fma_f32 v[0:1], v[0:1], v[10:11], v[20:21] op_sel_hi:[1,0,1]
	v_mov_b32_e32 v10, v15
	v_pk_fma_f32 v[12:13], v[2:3], v[14:15], v[22:23] op_sel_hi:[1,1,0] neg_lo:[0,0,1] neg_hi:[0,0,1]
	v_pk_fma_f32 v[10:11], v[2:3], v[10:11], v[24:25] op_sel_hi:[1,1,0]
	v_sub_f32_e32 v4, v16, v18
	v_mov_b32_e32 v6, v26
	v_mov_b32_e32 v0, v8
	v_mov_b32_e32 v2, v12
	v_mov_b32_e32 v3, v10
	s_branch .LBB0_1260

.LBB0_1332:
	s_andn2_saveexec_b64 s[6:7], s[6:7]
	s_cbranch_execz .LBB0_1352
	s_mov_b64 s[14:15], exec
	s_waitcnt lgkmcnt(0)
	v_mbcnt_lo_u32_b32 v1, s14, 0
	v_mbcnt_hi_u32_b32 v1, s15, v1
	v_cmp_eq_u32_e32 vcc, 0, v1
	s_and_saveexec_b64 s[16:17], vcc
	s_cbranch_execz .LBB0_1335
	s_bcnt1_i32_b64 s3, s[14:15]
	v_mov_b32_e32 v2, 0xed25000
	v_mov_b32_e32 v3, s3
	global_atomic_add v2, v2, v3, s[24:25] offset:1024 sc0

.LBB0_1536:
	s_andn2_saveexec_b64 s[6:7], s[6:7]
	s_cbranch_execz .LBB0_1556
	s_mov_b64 s[6:7], exec
	s_waitcnt lgkmcnt(0)
	v_mbcnt_lo_u32_b32 v1, s6, 0
	v_mbcnt_hi_u32_b32 v1, s7, v1
	v_cmp_eq_u32_e32 vcc, 0, v1
	s_and_saveexec_b64 s[8:9], vcc
	s_cbranch_execz .LBB0_1539
	s_bcnt1_i32_b64 s6, s[6:7]
	v_mov_b32_e32 v2, 0xed25000
	v_mov_b32_e32 v3, s6
	global_atomic_add v2, v2, v3, s[24:25] offset:1024 sc0
